# down/out GEMMs: waves 0-3 take the stagger-rebalancing barrier before the last tile's epilogue (phase-neutral padding)
# speedup vs baseline: 1.0058x; 1.0058x over previous
; #define LAS __attribute__((address_space(3)))
; __device__ __forceinline__ CArgs get_args() { CArgs p = (CArgs)__builtin_amdgcn_kernarg_segment_ptr(); asm volatile("" : "+s"(p)); return p; }
; __global__ void __launch_bounds__(NTHR, 2) mk_fwd(Args a_by_value) {
;     extern __shared__ __attribute__((aligned(16))) unsigned char lds_raw[];
;     LAS unsigned char* lds = (LAS unsigned char*)lds_raw;
;     cg::grid_group grid = cg::this_grid();
;     const int G = gridDim.x;
;     unsigned char* ws; { CArgs a0 = get_args(); ws = a0->ws; }
;     const int ph_lo = get_args()->ph_lo, ph_hi = get_args()->ph_hi;
;     float* rowss = (float*)(ws + WS_CTL + CTL_ROWSS);
;     bf16_t* U = (bf16_t*)(ws + WS_U); bf16_t* Hb = U; bf16_t* XB = (bf16_t*)(ws + WS_XB); bf16_t* Y = (bf16_t*)(ws + WS_Y);
;     unsigned char* wsw = ws + WS_W;
;     volatile LAS unsigned* xst = (volatile LAS unsigned*)(lds + LDS_BYTES - 16);
;     if (threadIdx.x < 4) xst[threadIdx.x] = 0u;
;     __syncthreads();
;     XcdBarrier xbar; xbar.bar = (unsigned*)(ws + WS_BAR); xbar.x = 0; xbar.st = xst;
;     if (USE_XCD_BAR && ph_hi - ph_lo > 1) xbar = xcd_barrier_post((unsigned*)(ws + WS_BAR), xst);
_Z6mk_fwd4Args:
	s_load_dwordx2 s[64:65], s[0:1], 0xf8
	v_writelane_b32 v253, s2, 0
	s_mov_b64 s[2:3], s[0:1]
	s_load_dwordx2 s[66:67], s[2:3], 0xe8
	s_mov_b64 s[2:3], s[0:1]
	s_load_dword s2, s[2:3], 0xf0
	v_and_b32_e32 v244, 0x3ff, v0
	v_cmp_gt_u32_e32 vcc, 4, v244
	s_waitcnt lgkmcnt(0)
	v_writelane_b32 v253, s2, 1
	s_mov_b64 s[2:3], s[0:1]
	s_load_dword s2, s[2:3], 0xf4
	s_waitcnt lgkmcnt(0)
	v_writelane_b32 v253, s2, 2
	s_add_u32 s2, s0, 0xf8
	v_writelane_b32 v253, s0, 3
	s_addc_u32 s3, s1, 0
	s_nop 0
	v_writelane_b32 v253, s1, 4
	v_writelane_b32 v253, s2, 5
	s_nop 1
	v_writelane_b32 v253, s3, 6
	s_and_saveexec_b64 s[0:1], vcc
	v_lshl_add_u32 v1, v244, 2, 0
	v_add_u32_e32 v1, 0x23ff0, v1
	v_mov_b32_e32 v2, 0
	ds_write_b32 v1, v2
	s_or_b64 exec, exec, s[0:1]
	s_add_u32 s0, s66, 0x180000
	v_readlane_b32 s2, v253, 1
	v_readlane_b32 s3, v253, 2
	s_addc_u32 s1, s67, 0
	s_sub_i32 s2, s3, s2
	s_mov_b32 s6, 0
	s_nop 3
	v_writelane_b32 v255, s6, 43
	s_nop 3
	s_nop 3
	v_writelane_b32 v255, s6, 43
	s_nop 3
	s_cmp_lt_i32 s2, 2
	v_cmp_eq_u32_e32 vcc, 0, v244
	s_waitcnt lgkmcnt(0)
	s_barrier
	s_cbranch_scc1 .LBB0_7
	s_getreg_b32 s2, hwreg(HW_REG_XCC_ID, 0, 4)
	s_and_b32 s6, s2, 15
	s_and_saveexec_b64 s[2:3], vcc
	s_cbranch_execz .LBB0_6
	s_mov_b64 s[4:5], exec
	v_mbcnt_lo_u32_b32 v1, s4, 0
	v_mbcnt_hi_u32_b32 v1, s5, v1
	v_cmp_eq_u32_e32 vcc, 0, v1
	s_and_b64 s[8:9], exec, vcc
	s_mov_b64 exec, s[8:9]
	s_cbranch_execz .LBB0_6
	s_lshl_b32 s7, s6, 8
	s_bcnt1_i32_b64 s4, s[4:5]
	v_mov_b32_e32 v1, s7
	v_mov_b32_e32 v2, s4
	global_atomic_add v1, v2, s[0:1] offset:1024

; template <class Epi, class Sched, bool ALIGN_EPI>
; __device__ __forceinline__ void gemm_phase(PG8_LAS unsigned char* lds, const Gemm g, const Sched& S, const Epi& E) {
;     ...
;     if constexpr (!ALIGN_EPI) { if (wr == 0) PG8_BAR; }
;     __device__ __forceinline__ void operator()(const f32x4 (&acc)[2][2][4][2], const pg8::Unit& u, int wr, int wc, int fr, int fq) const {
;         const int row0 = u.pm * 256 + wr * 64 + fr, col0 = u.pn * 256 + wc * 32 + 8 * fq;
;         f32x4 pre[4][2][2];
; #pragma unroll
;         for (int m = 0; m < 4; ++m)
; #pragma unroll
;             for (int bj = 0; bj < 2; ++bj) { const size_t off = (size_t)(row0 + m * 16) * DM + col0 + bj * 128;
;                 pre[m][bj][0] = *(const f32x4*)(base + off); pre[m][bj][1] = *(const f32x4*)(base + off + 4); }
; #pragma unroll
;         for (int ai = 0; ai < 2; ++ai)
; #pragma unroll
;             for (int m = 0; m < 4; ++m) {
;                 const int row = row0 + ai * 128 + m * 16; float part = 0.f;
;                 f32x4 v[2][2];
; #pragma unroll
;                 for (int bj = 0; bj < 2; ++bj) { v[bj][0] = pre[m][bj][0] + acc[ai][bj][m][0] * scale; v[bj][1] = pre[m][bj][1] + acc[ai][bj][m][1] * scale; }
;                 if (ai == 0) {
; #pragma unroll
;                     for (int bj = 0; bj < 2; ++bj) { const size_t off2 = (size_t)(row + 128) * DM + col0 + bj * 128;
;                         pre[m][bj][0] = *(const f32x4*)(base + off2); pre[m][bj][1] = *(const f32x4*)(base + off2 + 4); }
;                 }
; #pragma unroll
;                 for (int bj = 0; bj < 2; ++bj) {
;                     const size_t off = (size_t)row * DM + col0 + bj * 128;
;                     const f32x4 v0 = v[bj][0], v1 = v[bj][1];
;                     *(f32x4*)(out + off) = v0; *(f32x4*)(out + off + 4) = v1;
;                     u32x4 w; w.x = cvt_pk_bf16(v0[0], v0[1]); w.y = cvt_pk_bf16(v0[2], v0[3]); w.z = cvt_pk_bf16(v1[0], v1[1]); w.w = cvt_pk_bf16(v1[2], v1[3]);
;                     wt16(xb + (size_t)row * XLD + col0 + bj * 128, w);
;                     part += (v0[0] * v0[0] + v0[1] * v0[1]) + (v0[2] * v0[2] + v0[3] * v0[3]) + (v1[0] * v1[0] + v1[1] * v1[1]) + (v1[2] * v1[2] + v1[3] * v1[3]);
;                 }
;                 part += __shfl_xor(part, 16); part += __shfl_xor(part, 32);
;                 if (fq == 0) wt4f(ss + (size_t)row * 16 + u.pn * 4 + wc, part);
.LBB0_40:
	s_and_b64 s[98:99], exec, s[42:43]
	s_cbranch_scc0 .Lea_s0
	s_cmpk_gt_u32 s10, 0xff
	s_cbranch_scc1 .Lea_s0
	s_barrier
	s_mov_b32 s98, 1
	s_nop 0
	v_writelane_b32 v255, s98, 43
.Lea_s0:
	s_nop 0
	v_lshl_or_b32 v228, s48, 8, v234
	v_lshl_add_u32 v214, s50, 8, v194
	v_ashrrev_i32_e32 v229, 31, v228
	v_lshlrev_b64 v[212:213], 2, v[228:229]
	v_ashrrev_i32_e32 v215, 31, v214
	s_waitcnt lgkmcnt(0)
	v_lshl_add_u64 v[130:131], s[16:17], 0, v[212:213]
	v_lshlrev_b64 v[232:233], 12, v[214:215]
	v_lshl_add_u64 v[132:133], v[130:131], 0, v[232:233]
	global_load_dwordx4 v[178:181], v[132:133], off offset:16
	global_load_dwordx4 v[182:185], v[132:133], off
	global_load_dwordx4 v[216:219], v[132:133], off offset:528
	global_load_dwordx4 v[236:239], v[132:133], off offset:512
	v_and_b32_e32 v187, 64, v247
	v_xor_b32_e32 v186, 16, v247
	v_add_u32_e32 v187, 64, v187
	v_cmp_lt_i32_e32 vcc, v186, v187
	v_or_b32_e32 v226, 16, v214
	v_add_u32_e32 v210, 0x80, v214
	v_cndmask_b32_e32 v186, v247, v186, vcc
	v_lshlrev_b32_e32 v197, 2, v186
	v_xor_b32_e32 v186, 32, v247
	v_cmp_lt_i32_e32 vcc, v186, v187
	v_ashrrev_i32_e32 v227, 31, v226
	v_or_b32_e32 v222, 32, v214
	v_or_b32_e32 v208, 48, v214
	v_cndmask_b32_e32 v186, v247, v186, vcc
	v_ashrrev_i32_e32 v211, 31, v210
	v_lshlrev_b64 v[230:231], 12, v[226:227]
	v_ashrrev_i32_e32 v223, 31, v222
	v_ashrrev_i32_e32 v209, 31, v208
	v_lshlrev_b32_e32 v196, 2, v186
	v_lshl_add_u64 v[132:133], v[130:131], 0, v[230:231]
	v_lshlrev_b64 v[224:225], 12, v[222:223]
	v_lshlrev_b64 v[220:221], 12, v[208:209]
	global_load_dwordx4 v[166:169], v[132:133], off offset:16
	global_load_dwordx4 v[174:177], v[132:133], off
	global_load_dwordx4 v[162:165], v[132:133], off offset:528
	global_load_dwordx4 v[170:173], v[132:133], off offset:512
	v_lshl_add_u64 v[132:133], v[130:131], 0, v[224:225]
	v_lshl_add_u64 v[138:139], v[130:131], 0, v[220:221]
	global_load_dwordx4 v[150:153], v[132:133], off offset:16
	global_load_dwordx4 v[158:161], v[132:133], off
	global_load_dwordx4 v[146:149], v[132:133], off offset:528
	global_load_dwordx4 v[154:157], v[132:133], off offset:512
	global_load_dwordx4 v[134:137], v[138:139], off offset:16
	global_load_dwordx4 v[142:145], v[138:139], off
	s_nop 0
	global_load_dwordx4 v[130:133], v[138:139], off offset:528
	s_nop 0
	global_load_dwordx4 v[138:141], v[138:139], off offset:512
	s_mov_b32 s58, s62
	s_mov_b32 s59, s63
	s_lshl_b32 s44, s48, 2
	s_ashr_i32 s45, s44, 31
	s_waitcnt vmcnt(0)
	v_pk_add_f32 v[186:187], v[126:127], v[178:179]
	v_pk_add_f32 v[188:189], v[128:129], v[180:181]
	v_pk_add_f32 v[178:179], v[114:115], v[216:217]
	v_lshlrev_b64 v[216:217], 12, v[210:211]
	v_lshl_add_u64 v[114:115], s[16:17], 0, v[216:217]
	v_pk_add_f32 v[180:181], v[116:117], v[218:219]
	v_lshl_add_u64 v[218:219], v[114:115], 0, v[212:213]
	v_pk_add_f32 v[192:193], v[124:125], v[184:185]
	v_pk_add_f32 v[190:191], v[122:123], v[182:183]
	v_pk_add_f32 v[184:185], v[120:121], v[238:239]
	v_pk_add_f32 v[182:183], v[118:119], v[236:237]
	global_load_dwordx4 v[118:121], v[218:219], off offset:16
	global_load_dwordx4 v[114:117], v[218:219], off
	global_load_dwordx4 v[126:129], v[218:219], off offset:528
	global_load_dwordx4 v[122:125], v[218:219], off offset:512
	v_lshl_add_u64 v[236:237], s[16:17], 0, v[232:233]
	v_lshl_add_u64 v[240:241], v[236:237], 0, v[212:213]
	global_store_dwordx4 v[240:241], v[190:193], off
	global_store_dwordx4 v[240:241], v[186:189], off offset:16
	v_cvt_pk_bf16_f32 v236, v190, v191
	v_mul_f32_e32 v191, v191, v191
	v_fmac_f32_e32 v191, v190, v190
	v_mul_f32_e32 v190, v193, v193
	v_cvt_pk_bf16_f32 v238, v186, v187
	v_fmac_f32_e32 v190, v192, v192
	v_mul_f32_e32 v187, v187, v187
	v_lshlrev_b32_e32 v217, 1, v228
	v_add_f32_e32 v190, v191, v190
	v_fmac_f32_e32 v187, v186, v186
	v_add3_u32 v217, s5, v232, v217
	v_add_f32_e32 v186, v190, v187
	v_mul_f32_e32 v187, v189, v189
	v_cvt_pk_bf16_f32 v237, v192, v193
	v_cvt_pk_bf16_f32 v239, v188, v189
	v_subrev_u32_e32 v217, s66, v217
	v_fmac_f32_e32 v187, v188, v188
	buffer_store_dwordx4 v[236:239], v217, s[56:59], 0 offen sc1
	v_add_f32_e32 v190, v187, v186
	global_store_dwordx4 v[240:241], v[182:185], off offset:512
	global_store_dwordx4 v[240:241], v[178:181], off offset:528
	v_cvt_pk_bf16_f32 v186, v182, v183
	v_mul_f32_e32 v183, v183, v183
	v_fmac_f32_e32 v183, v182, v182
	v_mul_f32_e32 v182, v185, v185
	v_cvt_pk_bf16_f32 v188, v178, v179
	v_fmac_f32_e32 v182, v184, v184
	v_mul_f32_e32 v179, v179, v179
	v_add_f32_e32 v182, v183, v182
	v_fmac_f32_e32 v179, v178, v178
	v_add_f32_e32 v178, v182, v179
	v_mul_f32_e32 v179, v181, v181
	v_fmac_f32_e32 v179, v180, v180
	v_add_f32_e32 v178, v179, v178
	v_add_f32_e32 v178, v190, v178
	ds_bpermute_b32 v179, v197, v178
	v_cvt_pk_bf16_f32 v187, v184, v185
	v_cvt_pk_bf16_f32 v189, v180, v181
	buffer_store_dwordx4 v[186:189], v217, s[56:59], 0 offen offset:256 sc1
	s_waitcnt lgkmcnt(0)
	v_add_f32_e32 v178, v178, v179
	ds_bpermute_b32 v179, v196, v178
	s_and_saveexec_b64 s[2:3], s[40:41]
	s_cbranch_execz .LBB0_42
	s_waitcnt lgkmcnt(0)
	v_add_f32_e32 v180, v178, v179
	v_lshlrev_b64 v[178:179], 6, v[214:215]
	v_lshl_add_u64 v[178:179], s[66:67], 0, v[178:179]
	v_lshl_add_u64 v[178:179], s[44:45], 2, v[178:179]
	s_lshl_b32 s34, s51, 2
	v_lshl_add_u64 v[178:179], v[178:179], 0, s[34:35]
	global_store_dword v[178:179], v180, off sc1

; #define PG8_WAIT_V(n) asm volatile("s_waitcnt vmcnt(" #n ")" ::: "memory")
; #define PG8_BAR __builtin_amdgcn_s_barrier()
; template <class Epi, class Sched, bool ALIGN_EPI>
; __device__ __forceinline__ void gemm_phase(PG8_LAS unsigned char* lds, const Gemm g, const Sched& S, const Epi& E) {
;     ...
;     PG8_WAIT_V(0);
;     if constexpr (!ALIGN_EPI) { if (wr == 0) PG8_BAR; }
;     PG8_BAR;
.LBB0_56:
	s_waitcnt vmcnt(0)
	s_cmpk_gt_u32 s10, 0xff
	v_readlane_b32 s22, v255, 10
	v_readlane_b32 s23, v255, 11
	s_cbranch_scc1 .LBB0_58
	v_readlane_b32 s98, v255, 43
	s_mov_b32 s99, 0
	s_nop 1
	v_writelane_b32 v255, s99, 43
	s_cmp_eq_u32 s98, 1
	s_cbranch_scc1 .LBB0_58
	s_barrier

; #define PG8_STAGE(bufoff, gbase, voff) do { _Pragma("unroll") for (int _i = 0; _i < 2; ++_i) \
;         __builtin_amdgcn_global_load_lds((const unsigned*)((const char*)(gbase) + (voff)[_i]), (PG8_LAS unsigned*)(lds + (bufoff) + ldsw + _i * 8192), 16, 0, 0); } while (0)
; #define PG8_LDA(dst, b, h) do { _Pragma("unroll") for (int m = 0; m < 4; ++m) _Pragma("unroll") for (int k = 0; k < 2; ++k) dst[m][k] = *(const PG8_LAS bf16x8*)(lds + PG8_SA(b, h) + aoff + m * 2048 + k * 1024); } while (0)
; #define PG8_LDB(dst, b, h) do { _Pragma("unroll") for (int n = 0; n < 2; ++n) _Pragma("unroll") for (int k = 0; k < 2; ++k) dst[n][k] = *(const PG8_LAS bf16x8*)(lds + PG8_SB(b, h) + boff + n * 2048 + k * 1024); } while (0)
; #define PG8_MMA(ai, bj, At, Bt) do { __builtin_amdgcn_s_setprio(1); _Pragma("unroll") for (int m = 0; m < 4; ++m) _Pragma("unroll") for (int n = 0; n < 2; ++n) _Pragma("unroll") for (int k = 0; k < 2; ++k) \
;         acc[ai][bj][m][n] = __builtin_amdgcn_mfma_f32_16x16x32_bf16(Bt[n][k], At[m][k], acc[ai][bj][m][n], 0, 0, 0); __builtin_amdgcn_s_setprio(0); } while (0)
; template <class Epi, class Sched, bool ALIGN_EPI>
; __device__ __forceinline__ void gemm_phase(PG8_LAS unsigned char* lds, const Gemm g, const Sched& S, const Epi& E) {
;     ...
;         for (int t = 0; t < nt; t += 2) {
;             const bool last = (t == nt - 2);
;             const char* a1 = cA + (size_t)(t + 1) * kstep;
;             const char* a2 = last ? nA : cA + (size_t)(t + 2) * kstep; const char* b2 = last ? nB : cB + (size_t)(t + 2) * kstep;
;             const char* a3 = a2 + kstep; const char* b3 = b2 + kstep;
;             PG8_LDB(B0, 0, 0); PG8_LDB(B1, 0, 1); PG8_SCHED; PG8_LDA(At, 0, 0); PG8_STAGE(PG8_SA(1, 1), a1 + hstepA, voffA);
;             PG8_WAIT_V(8); PG8_WAIT_L(0); PG8_BAR; PG8_MMA(0, 0, At, B0); PG8_MMA(0, 1, At, B1); PG8_BAR; PG8_SCHED;
;             PG8_LDA(At, 0, 1); PG8_STAGE(PG8_SB(0, 0), b2, voffB); PG8_STAGE(PG8_SB(0, 1), b2 + hstepB, voffB); PG8_STAGE(PG8_SA(0, 0), a2, voffA);
;             PG8_WAIT_V(8); PG8_WAIT_L(0); PG8_BAR; PG8_MMA(1, 0, At, B0); PG8_MMA(1, 1, At, B1); PG8_BAR; PG8_SCHED;
;             PG8_LDB(B0, 1, 0); PG8_LDB(B1, 1, 1); PG8_SCHED; PG8_LDA(At, 1, 0); PG8_STAGE(PG8_SA(0, 1), a2 + hstepA, voffA);
;             PG8_WAIT_V(8); PG8_WAIT_L(0); PG8_BAR; PG8_MMA(0, 0, At, B0); PG8_MMA(0, 1, At, B1); PG8_BAR; PG8_SCHED;
.LBB0_334:
	s_add_i32 s59, s26, 2
	s_add_u32 s27, s44, 0xfff00080
	s_addc_u32 s28, s45, -1
	s_add_i32 s92, 0, 0x10000
	s_cmp_eq_u32 s89, s26
	s_cselect_b32 s29, s2, s28
	s_cselect_b32 s28, s3, s27
	s_cselect_b32 s27, s21, s58
	s_cselect_b32 s26, s23, s34
	s_add_i32 vcc_lo, 0, 0x14000
	v_add_u32_e32 v152, s92, v249
	v_add_u32_e32 v168, vcc_lo, v249
	ds_read_b128 v[140:143], v152
	ds_read_b128 v[144:147], v152 offset:1024
	ds_read_b128 v[148:151], v152 offset:2048
	ds_read_b128 v[152:155], v152 offset:3072
	ds_read_b128 v[156:159], v168
	ds_read_b128 v[160:163], v168 offset:1024
	ds_read_b128 v[164:167], v168 offset:2048
	ds_read_b128 v[168:171], v168 offset:3072
	v_lshl_add_u64 v[192:193], s[44:45], 0, v[136:137]
	s_add_i32 m0, s37, 0xc000
	ds_read_b128 v[172:175], v195
	ds_read_b128 v[176:179], v195 offset:1024
	ds_read_b128 v[180:183], v195 offset:2048
	ds_read_b128 v[184:187], v195 offset:3072
	ds_read_b128 v[188:191], v195 offset:4096
	ds_read_b128 v[196:199], v195 offset:5120
	ds_read_b128 v[200:203], v195 offset:6144
	ds_read_b128 v[204:207], v195 offset:7168
	global_load_lds_dwordx4 v[192:193], off
	v_lshl_add_u64 v[192:193], s[44:45], 0, v[138:139]
	s_add_i32 m0, s37, 0xe000
	s_nop 0
	global_load_lds_dwordx4 v[192:193], off
	s_waitcnt vmcnt(8)
	s_waitcnt lgkmcnt(0)
	s_barrier
	s_setprio 1
	s_waitcnt lgkmcnt(0)
	v_mfma_f32_16x16x32_bf16 v[126:129], v[140:143], v[172:175], v[126:129]
	v_mfma_f32_16x16x32_bf16 v[122:125], v[148:151], v[172:175], v[122:125]
	v_mfma_f32_16x16x32_bf16 v[118:121], v[140:143], v[180:183], v[118:121]
	v_mfma_f32_16x16x32_bf16 v[114:117], v[148:151], v[180:183], v[114:117]
	v_mfma_f32_16x16x32_bf16 v[106:109], v[140:143], v[188:191], v[106:109]
	v_mfma_f32_16x16x32_bf16 v[98:101], v[148:151], v[188:191], v[98:101]
	v_mfma_f32_16x16x32_bf16 v[90:93], v[140:143], v[200:203], v[90:93]
	v_mfma_f32_16x16x32_bf16 v[82:85], v[148:151], v[200:203], v[82:85]
	v_mfma_f32_16x16x32_bf16 v[126:129], v[144:147], v[176:179], v[126:129]
	v_mfma_f32_16x16x32_bf16 v[122:125], v[152:155], v[176:179], v[122:125]
	v_mfma_f32_16x16x32_bf16 v[118:121], v[144:147], v[184:187], v[118:121]
	v_mfma_f32_16x16x32_bf16 v[114:117], v[152:155], v[184:187], v[114:117]
	v_mfma_f32_16x16x32_bf16 v[106:109], v[144:147], v[196:199], v[106:109]
	v_mfma_f32_16x16x32_bf16 v[98:101], v[152:155], v[196:199], v[98:101]
	v_mfma_f32_16x16x32_bf16 v[90:93], v[144:147], v[204:207], v[90:93]
	v_mfma_f32_16x16x32_bf16 v[82:85], v[152:155], v[204:207], v[82:85]
	s_setprio 0
	s_setprio 1
	v_mfma_f32_16x16x32_bf16 v[110:113], v[156:159], v[172:175], v[110:113]
	v_mfma_f32_16x16x32_bf16 v[102:105], v[164:167], v[172:175], v[102:105]
	v_mfma_f32_16x16x32_bf16 v[94:97], v[156:159], v[180:183], v[94:97]
	v_mfma_f32_16x16x32_bf16 v[86:89], v[164:167], v[180:183], v[86:89]
	v_mfma_f32_16x16x32_bf16 v[78:81], v[156:159], v[188:191], v[78:81]
	v_mfma_f32_16x16x32_bf16 v[74:77], v[164:167], v[188:191], v[74:77]
	v_mfma_f32_16x16x32_bf16 v[70:73], v[156:159], v[200:203], v[70:73]
	v_mfma_f32_16x16x32_bf16 v[66:69], v[164:167], v[200:203], v[66:69]
	v_mfma_f32_16x16x32_bf16 v[110:113], v[160:163], v[176:179], v[110:113]
	v_mfma_f32_16x16x32_bf16 v[102:105], v[168:171], v[176:179], v[102:105]
	v_mfma_f32_16x16x32_bf16 v[94:97], v[160:163], v[184:187], v[94:97]
	v_mfma_f32_16x16x32_bf16 v[86:89], v[168:171], v[184:187], v[86:89]
	v_mfma_f32_16x16x32_bf16 v[78:81], v[160:163], v[196:199], v[78:81]
	v_mfma_f32_16x16x32_bf16 v[74:77], v[168:171], v[196:199], v[74:77]
	v_mfma_f32_16x16x32_bf16 v[70:73], v[160:163], v[204:207], v[70:73]
	v_mfma_f32_16x16x32_bf16 v[66:69], v[168:171], v[204:207], v[66:69]
	s_setprio 0
	s_barrier
	s_add_i32 s92, s92, s13
	v_lshl_add_u64 v[192:193], s[26:27], 0, v[0:1]
	s_mov_b32 m0, s92
	ds_read_b128 v[172:175], v195 offset:16384
	ds_read_b128 v[176:179], v195 offset:17408
	ds_read_b128 v[180:183], v195 offset:18432
	ds_read_b128 v[184:187], v195 offset:19456
	ds_read_b128 v[188:191], v195 offset:20480
	ds_read_b128 v[196:199], v195 offset:21504
	ds_read_b128 v[200:203], v195 offset:22528
	ds_read_b128 v[204:207], v195 offset:23552
	global_load_lds_dwordx4 v[192:193], off
	s_add_i32 m0, s92, 0x2000
	s_add_u32 s92, s26, 0x100000
	v_lshl_add_u64 v[208:209], s[26:27], 0, v[134:135]
	s_addc_u32 s93, s27, 0
	s_add_i32 vcc_lo, vcc_lo, s13
	global_load_lds_dwordx4 v[208:209], off
	v_lshl_add_u64 v[210:211], s[92:93], 0, v[0:1]
	s_mov_b32 m0, vcc_lo
	v_lshl_add_u64 v[212:213], s[28:29], 0, v[132:133]
	global_load_lds_dwordx4 v[210:211], off
	v_lshl_add_u64 v[210:211], s[92:93], 0, v[134:135]
	s_add_i32 m0, vcc_lo, 0x2000
	s_nop 0
	global_load_lds_dwordx4 v[210:211], off
	v_lshl_add_u64 v[210:211], s[28:29], 0, v[130:131]
	s_mov_b32 m0, s37
	s_nop 0
	global_load_lds_dwordx4 v[210:211], off
	s_mov_b32 m0, s49
	s_nop 0
	global_load_lds_dwordx4 v[212:213], off
	s_waitcnt vmcnt(8)
	s_waitcnt lgkmcnt(0)
	s_barrier
; #define PG8_STAGE(bufoff, gbase, voff) do { _Pragma("unroll") for (int _i = 0; _i < 2; ++_i) \
;         __builtin_amdgcn_global_load_lds((const unsigned*)((const char*)(gbase) + (voff)[_i]), (PG8_LAS unsigned*)(lds + (bufoff) + ldsw + _i * 8192), 16, 0, 0); } while (0)
; #define PG8_LDA(dst, b, h) do { _Pragma("unroll") for (int m = 0; m < 4; ++m) _Pragma("unroll") for (int k = 0; k < 2; ++k) dst[m][k] = *(const PG8_LAS bf16x8*)(lds + PG8_SA(b, h) + aoff + m * 2048 + k * 1024); } while (0)
; #define PG8_LDB(dst, b, h) do { _Pragma("unroll") for (int n = 0; n < 2; ++n) _Pragma("unroll") for (int k = 0; k < 2; ++k) dst[n][k] = *(const PG8_LAS bf16x8*)(lds + PG8_SB(b, h) + boff + n * 2048 + k * 1024); } while (0)
; #define PG8_MMA(ai, bj, At, Bt) do { __builtin_amdgcn_s_setprio(1); _Pragma("unroll") for (int m = 0; m < 4; ++m) _Pragma("unroll") for (int n = 0; n < 2; ++n) _Pragma("unroll") for (int k = 0; k < 2; ++k) \
;         acc[ai][bj][m][n] = __builtin_amdgcn_mfma_f32_16x16x32_bf16(Bt[n][k], At[m][k], acc[ai][bj][m][n], 0, 0, 0); __builtin_amdgcn_s_setprio(0); } while (0)
; #define PG8_WAIT_V(n) asm volatile("s_waitcnt vmcnt(" #n ")" ::: "memory")
; #define PG8_WAIT_L(n) asm volatile("s_waitcnt lgkmcnt(" #n ")" ::: "memory")
; #define PG8_BAR __builtin_amdgcn_s_barrier()
; #define PG8_SCHED __builtin_amdgcn_sched_barrier(0)
; template <class Epi, class Sched, bool ALIGN_EPI>
; __device__ __forceinline__ void gemm_phase(PG8_LAS unsigned char* lds, const Gemm g, const Sched& S, const Epi& E) {
;     ...
;             PG8_WAIT_V(8); PG8_WAIT_L(0); PG8_BAR; PG8_MMA(1, 0, At, B0); PG8_MMA(1, 1, At, B1); PG8_BAR; PG8_SCHED;
;             PG8_LDB(B0, 1, 0); PG8_LDB(B1, 1, 1); PG8_SCHED; PG8_LDA(At, 1, 0); PG8_STAGE(PG8_SA(0, 1), a2 + hstepA, voffA);
;             PG8_WAIT_V(8); PG8_WAIT_L(0); PG8_BAR; PG8_MMA(0, 0, At, B0); PG8_MMA(0, 1, At, B1); PG8_BAR; PG8_SCHED;
	s_setprio 1
	s_waitcnt lgkmcnt(0)
	v_mfma_f32_16x16x32_bf16 v[62:65], v[140:143], v[172:175], v[62:65]
	v_mfma_f32_16x16x32_bf16 v[58:61], v[148:151], v[172:175], v[58:61]
	v_mfma_f32_16x16x32_bf16 v[54:57], v[140:143], v[180:183], v[54:57]
	v_mfma_f32_16x16x32_bf16 v[50:53], v[148:151], v[180:183], v[50:53]
	v_mfma_f32_16x16x32_bf16 v[38:41], v[140:143], v[188:191], v[38:41]
	v_mfma_f32_16x16x32_bf16 v[34:37], v[148:151], v[188:191], v[34:37]
	v_mfma_f32_16x16x32_bf16 v[22:25], v[140:143], v[200:203], v[22:25]
	v_mfma_f32_16x16x32_bf16 v[18:21], v[148:151], v[200:203], v[18:21]
	v_mfma_f32_16x16x32_bf16 v[62:65], v[144:147], v[176:179], v[62:65]
	v_mfma_f32_16x16x32_bf16 v[58:61], v[152:155], v[176:179], v[58:61]
	v_mfma_f32_16x16x32_bf16 v[54:57], v[144:147], v[184:187], v[54:57]
	v_mfma_f32_16x16x32_bf16 v[50:53], v[152:155], v[184:187], v[50:53]
	v_mfma_f32_16x16x32_bf16 v[38:41], v[144:147], v[196:199], v[38:41]
	v_mfma_f32_16x16x32_bf16 v[34:37], v[152:155], v[196:199], v[34:37]
	v_mfma_f32_16x16x32_bf16 v[22:25], v[144:147], v[204:207], v[22:25]
	v_mfma_f32_16x16x32_bf16 v[18:21], v[152:155], v[204:207], v[18:21]
	s_setprio 0
	s_setprio 1
	v_mfma_f32_16x16x32_bf16 v[46:49], v[156:159], v[172:175], v[46:49]
	v_mfma_f32_16x16x32_bf16 v[42:45], v[164:167], v[172:175], v[42:45]
	v_mfma_f32_16x16x32_bf16 v[30:33], v[156:159], v[180:183], v[30:33]
	v_mfma_f32_16x16x32_bf16 v[26:29], v[164:167], v[180:183], v[26:29]
	v_mfma_f32_16x16x32_bf16 v[14:17], v[156:159], v[188:191], v[14:17]
	v_mfma_f32_16x16x32_bf16 v[10:13], v[164:167], v[188:191], v[10:13]
	v_mfma_f32_16x16x32_bf16 v[6:9], v[156:159], v[200:203], v[6:9]
	v_mfma_f32_16x16x32_bf16 v[2:5], v[164:167], v[200:203], v[2:5]
	v_mfma_f32_16x16x32_bf16 v[46:49], v[160:163], v[176:179], v[46:49]
	v_mfma_f32_16x16x32_bf16 v[42:45], v[168:171], v[176:179], v[42:45]
	v_mfma_f32_16x16x32_bf16 v[30:33], v[160:163], v[184:187], v[30:33]
	v_mfma_f32_16x16x32_bf16 v[26:29], v[168:171], v[184:187], v[26:29]
	v_mfma_f32_16x16x32_bf16 v[14:17], v[160:163], v[196:199], v[14:17]
	v_mfma_f32_16x16x32_bf16 v[10:13], v[168:171], v[196:199], v[10:13]
	v_mfma_f32_16x16x32_bf16 v[6:9], v[160:163], v[204:207], v[6:9]
	v_mfma_f32_16x16x32_bf16 v[2:5], v[168:171], v[204:207], v[2:5]
	s_setprio 0
	s_barrier
	s_add_i32 s92, 0, 0x18000
	s_add_i32 s93, 0, 0x1c000
	v_add_u32_e32 v152, s92, v249
	v_add_u32_e32 v168, s93, v249
	ds_read_b128 v[140:143], v152
	ds_read_b128 v[144:147], v152 offset:1024
	ds_read_b128 v[148:151], v152 offset:2048
	ds_read_b128 v[152:155], v152 offset:3072
	ds_read_b128 v[156:159], v168
	ds_read_b128 v[160:163], v168 offset:1024
	ds_read_b128 v[164:167], v168 offset:2048
	ds_read_b128 v[168:171], v168 offset:3072
	s_add_u32 s28, s28, 0x100000
	s_addc_u32 s29, s29, 0
	s_mov_b32 m0, s51
	v_lshl_add_u64 v[214:215], s[28:29], 0, v[130:131]
	ds_read_b128 v[172:175], v195 offset:32768
	ds_read_b128 v[176:179], v195 offset:33792
	ds_read_b128 v[180:183], v195 offset:34816
	ds_read_b128 v[184:187], v195 offset:35840
	ds_read_b128 v[188:191], v195 offset:36864
	ds_read_b128 v[196:199], v195 offset:37888
	ds_read_b128 v[200:203], v195 offset:38912
	ds_read_b128 v[204:207], v195 offset:39936
	global_load_lds_dwordx4 v[214:215], off
	v_lshl_add_u64 v[214:215], s[28:29], 0, v[132:133]
	s_mov_b32 m0, s54
	s_nop 0
	global_load_lds_dwordx4 v[214:215], off
	s_waitcnt vmcnt(8)
	s_waitcnt lgkmcnt(0)
	s_barrier
	s_setprio 1
	s_waitcnt lgkmcnt(0)
	v_mfma_f32_16x16x32_bf16 v[126:129], v[140:143], v[172:175], v[126:129]
	v_mfma_f32_16x16x32_bf16 v[122:125], v[148:151], v[172:175], v[122:125]
	v_mfma_f32_16x16x32_bf16 v[118:121], v[140:143], v[180:183], v[118:121]
	v_mfma_f32_16x16x32_bf16 v[114:117], v[148:151], v[180:183], v[114:117]
	v_mfma_f32_16x16x32_bf16 v[106:109], v[140:143], v[188:191], v[106:109]
	v_mfma_f32_16x16x32_bf16 v[98:101], v[148:151], v[188:191], v[98:101]
	v_mfma_f32_16x16x32_bf16 v[90:93], v[140:143], v[200:203], v[90:93]
	v_mfma_f32_16x16x32_bf16 v[82:85], v[148:151], v[200:203], v[82:85]
	v_mfma_f32_16x16x32_bf16 v[126:129], v[144:147], v[176:179], v[126:129]
	v_mfma_f32_16x16x32_bf16 v[122:125], v[152:155], v[176:179], v[122:125]
	v_mfma_f32_16x16x32_bf16 v[118:121], v[144:147], v[184:187], v[118:121]
	v_mfma_f32_16x16x32_bf16 v[114:117], v[152:155], v[184:187], v[114:117]
	v_mfma_f32_16x16x32_bf16 v[106:109], v[144:147], v[196:199], v[106:109]
	v_mfma_f32_16x16x32_bf16 v[98:101], v[152:155], v[196:199], v[98:101]
	v_mfma_f32_16x16x32_bf16 v[90:93], v[144:147], v[204:207], v[90:93]
	v_mfma_f32_16x16x32_bf16 v[82:85], v[152:155], v[204:207], v[82:85]
	s_setprio 0
	s_setprio 1
	v_mfma_f32_16x16x32_bf16 v[110:113], v[156:159], v[172:175], v[110:113]
	v_mfma_f32_16x16x32_bf16 v[102:105], v[164:167], v[172:175], v[102:105]
	v_mfma_f32_16x16x32_bf16 v[94:97], v[156:159], v[180:183], v[94:97]
	v_mfma_f32_16x16x32_bf16 v[86:89], v[164:167], v[180:183], v[86:89]
	v_mfma_f32_16x16x32_bf16 v[78:81], v[156:159], v[188:191], v[78:81]
	v_mfma_f32_16x16x32_bf16 v[74:77], v[164:167], v[188:191], v[74:77]
	v_mfma_f32_16x16x32_bf16 v[70:73], v[156:159], v[200:203], v[70:73]
	v_mfma_f32_16x16x32_bf16 v[66:69], v[164:167], v[200:203], v[66:69]
	v_mfma_f32_16x16x32_bf16 v[110:113], v[160:163], v[176:179], v[110:113]
	v_mfma_f32_16x16x32_bf16 v[102:105], v[168:171], v[176:179], v[102:105]
	v_mfma_f32_16x16x32_bf16 v[94:97], v[160:163], v[184:187], v[94:97]
	v_mfma_f32_16x16x32_bf16 v[86:89], v[168:171], v[184:187], v[86:89]
	v_mfma_f32_16x16x32_bf16 v[78:81], v[160:163], v[196:199], v[78:81]
	v_mfma_f32_16x16x32_bf16 v[74:77], v[168:171], v[196:199], v[74:77]
	v_mfma_f32_16x16x32_bf16 v[70:73], v[160:163], v[204:207], v[70:73]
	v_mfma_f32_16x16x32_bf16 v[66:69], v[168:171], v[204:207], v[66:69]
	s_setprio 0
	s_barrier
; #define PG8_STAGE(bufoff, gbase, voff) do { _Pragma("unroll") for (int _i = 0; _i < 2; ++_i) \
;         __builtin_amdgcn_global_load_lds((const unsigned*)((const char*)(gbase) + (voff)[_i]), (PG8_LAS unsigned*)(lds + (bufoff) + ldsw + _i * 8192), 16, 0, 0); } while (0)
; #define PG8_LDA(dst, b, h) do { _Pragma("unroll") for (int m = 0; m < 4; ++m) _Pragma("unroll") for (int k = 0; k < 2; ++k) dst[m][k] = *(const PG8_LAS bf16x8*)(lds + PG8_SA(b, h) + aoff + m * 2048 + k * 1024); } while (0)
; #define PG8_MMA(ai, bj, At, Bt) do { __builtin_amdgcn_s_setprio(1); _Pragma("unroll") for (int m = 0; m < 4; ++m) _Pragma("unroll") for (int n = 0; n < 2; ++n) _Pragma("unroll") for (int k = 0; k < 2; ++k) \
;         acc[ai][bj][m][n] = __builtin_amdgcn_mfma_f32_16x16x32_bf16(Bt[n][k], At[m][k], acc[ai][bj][m][n], 0, 0, 0); __builtin_amdgcn_s_setprio(0); } while (0)
; #define PG8_WAIT_V(n) asm volatile("s_waitcnt vmcnt(" #n ")" ::: "memory")
; #define PG8_WAIT_L(n) asm volatile("s_waitcnt lgkmcnt(" #n ")" ::: "memory")
; #define PG8_BAR __builtin_amdgcn_s_barrier()
; #define PG8_SCHED __builtin_amdgcn_sched_barrier(0)
; template <class Epi, class Sched, bool ALIGN_EPI>
; __device__ __forceinline__ void gemm_phase(PG8_LAS unsigned char* lds, const Gemm g, const Sched& S, const Epi& E) {
;     ...
;             PG8_LDA(At, 1, 1); PG8_STAGE(PG8_SB(1, 0), b3, voffB); PG8_STAGE(PG8_SB(1, 1), b3 + hstepB, voffB); PG8_STAGE(PG8_SA(1, 0), a3, voffA);
;             PG8_WAIT_V(8); PG8_WAIT_L(0); PG8_BAR; PG8_MMA(1, 0, At, B0); PG8_MMA(1, 1, At, B1); PG8_BAR; PG8_SCHED;
;         }
;         if constexpr (ALIGN_EPI) { if (wr == 0) PG8_BAR; }
;     ...
;     if constexpr (!ALIGN_EPI) { if (wr == 0) PG8_BAR; }
	s_add_i32 s28, s92, s13
	v_lshl_add_u64 v[192:193], v[192:193], 0, s[80:81]
	s_mov_b32 m0, s28
	ds_read_b128 v[172:175], v195 offset:49152
	ds_read_b128 v[176:179], v195 offset:50176
	ds_read_b128 v[180:183], v195 offset:51200
	ds_read_b128 v[184:187], v195 offset:52224
	ds_read_b128 v[188:191], v195 offset:53248
	ds_read_b128 v[196:199], v195 offset:54272
	ds_read_b128 v[200:203], v195 offset:55296
	ds_read_b128 v[204:207], v195 offset:56320
	global_load_lds_dwordx4 v[192:193], off
	s_add_i32 m0, s28, 0x2000
	s_add_u32 s26, s26, 0x100080
	v_lshl_add_u64 v[192:193], v[208:209], 0, s[80:81]
	s_addc_u32 s27, s27, 0
	s_add_i32 s28, s93, s13
	global_load_lds_dwordx4 v[192:193], off
	v_lshl_add_u64 v[192:193], s[26:27], 0, v[0:1]
	s_mov_b32 m0, s28
	s_nop 0
	global_load_lds_dwordx4 v[192:193], off
	v_lshl_add_u64 v[192:193], s[26:27], 0, v[134:135]
	s_add_i32 m0, s28, 0x2000
	s_nop 0
	global_load_lds_dwordx4 v[192:193], off
	v_lshl_add_u64 v[192:193], v[210:211], 0, s[80:81]
	s_mov_b32 m0, s61
	s_nop 0
	global_load_lds_dwordx4 v[192:193], off
	v_lshl_add_u64 v[192:193], v[212:213], 0, s[80:81]
	s_mov_b32 m0, s88
	s_nop 0
	global_load_lds_dwordx4 v[192:193], off
	s_waitcnt vmcnt(8)
	s_waitcnt lgkmcnt(0)
	s_barrier
	s_setprio 1
	s_waitcnt lgkmcnt(0)
	v_mfma_f32_16x16x32_bf16 v[62:65], v[140:143], v[172:175], v[62:65]
	v_mfma_f32_16x16x32_bf16 v[58:61], v[148:151], v[172:175], v[58:61]
	v_mfma_f32_16x16x32_bf16 v[54:57], v[140:143], v[180:183], v[54:57]
	v_mfma_f32_16x16x32_bf16 v[50:53], v[148:151], v[180:183], v[50:53]
	v_mfma_f32_16x16x32_bf16 v[38:41], v[140:143], v[188:191], v[38:41]
	v_mfma_f32_16x16x32_bf16 v[34:37], v[148:151], v[188:191], v[34:37]
	v_mfma_f32_16x16x32_bf16 v[22:25], v[140:143], v[200:203], v[22:25]
	v_mfma_f32_16x16x32_bf16 v[18:21], v[148:151], v[200:203], v[18:21]
	v_mfma_f32_16x16x32_bf16 v[62:65], v[144:147], v[176:179], v[62:65]
	v_mfma_f32_16x16x32_bf16 v[58:61], v[152:155], v[176:179], v[58:61]
	v_mfma_f32_16x16x32_bf16 v[54:57], v[144:147], v[184:187], v[54:57]
	v_mfma_f32_16x16x32_bf16 v[50:53], v[152:155], v[184:187], v[50:53]
	v_mfma_f32_16x16x32_bf16 v[38:41], v[144:147], v[196:199], v[38:41]
	v_mfma_f32_16x16x32_bf16 v[34:37], v[152:155], v[196:199], v[34:37]
	v_mfma_f32_16x16x32_bf16 v[22:25], v[144:147], v[204:207], v[22:25]
	v_mfma_f32_16x16x32_bf16 v[18:21], v[152:155], v[204:207], v[18:21]
	s_setprio 0
	s_setprio 1
	v_mfma_f32_16x16x32_bf16 v[46:49], v[156:159], v[172:175], v[46:49]
	v_mfma_f32_16x16x32_bf16 v[42:45], v[164:167], v[172:175], v[42:45]
	v_mfma_f32_16x16x32_bf16 v[30:33], v[156:159], v[180:183], v[30:33]
	v_mfma_f32_16x16x32_bf16 v[26:29], v[164:167], v[180:183], v[26:29]
	v_mfma_f32_16x16x32_bf16 v[14:17], v[156:159], v[188:191], v[14:17]
	v_mfma_f32_16x16x32_bf16 v[10:13], v[164:167], v[188:191], v[10:13]
	v_mfma_f32_16x16x32_bf16 v[6:9], v[156:159], v[200:203], v[6:9]
	v_mfma_f32_16x16x32_bf16 v[2:5], v[164:167], v[200:203], v[2:5]
	v_mfma_f32_16x16x32_bf16 v[46:49], v[160:163], v[176:179], v[46:49]
	v_mfma_f32_16x16x32_bf16 v[42:45], v[168:171], v[176:179], v[42:45]
	v_mfma_f32_16x16x32_bf16 v[30:33], v[160:163], v[184:187], v[30:33]
	v_mfma_f32_16x16x32_bf16 v[26:29], v[168:171], v[184:187], v[26:29]
	v_mfma_f32_16x16x32_bf16 v[14:17], v[160:163], v[196:199], v[14:17]
	v_mfma_f32_16x16x32_bf16 v[10:13], v[168:171], v[196:199], v[10:13]
	v_mfma_f32_16x16x32_bf16 v[6:9], v[160:163], v[204:207], v[6:9]
	v_mfma_f32_16x16x32_bf16 v[2:5], v[168:171], v[204:207], v[2:5]
	s_setprio 0
	s_barrier
	s_add_u32 s44, s44, 0x100
	s_addc_u32 s45, s45, 0
	s_add_u32 s34, s34, 0x100
	s_addc_u32 s58, s58, 0
	s_cmp_ge_i32 s59, s60
	s_mov_b32 s26, s59
	s_cbranch_scc0 .LBB0_334
	s_and_b64 s[98:99], exec, s[42:43]
	s_cbranch_scc0 .Lea_s3
	s_cmpk_gt_u32 s10, 0xff
	s_cbranch_scc1 .Lea_s3
	s_barrier
	s_mov_b32 s98, 1
	s_nop 0
	v_writelane_b32 v255, s98, 43
;     __device__ __forceinline__ void operator()(const f32x4 (&acc)[2][2][4][2], const pg8::Unit& u, int wr, int wc, int fr, int fq) const {
;     ...
;                 for (int bj = 0; bj < 2; ++bj) { v[bj][0] = pre[m][bj][0] + acc[ai][bj][m][0] * scale; v[bj][1] = pre[m][bj][1] + acc[ai][bj][m][1] * scale; }
.Lea_s3:
	s_nop 0
	v_pk_mul_f32 v[192:193], v[128:129], 0.5 op_sel_hi:[1,0]
	v_pk_mul_f32 v[214:215], v[126:127], 0.5 op_sel_hi:[1,0]
	v_pk_mul_f32 v[230:231], v[124:125], 0.5 op_sel_hi:[1,0]
	v_pk_mul_f32 v[232:233], v[122:123], 0.5 op_sel_hi:[1,0]
	v_pk_mul_f32 v[234:235], v[112:113], 0.5 op_sel_hi:[1,0]
	v_pk_mul_f32 v[236:237], v[110:111], 0.5 op_sel_hi:[1,0]
	v_pk_mul_f32 v[238:239], v[104:105], 0.5 op_sel_hi:[1,0]
	v_pk_mul_f32 v[240:241], v[102:103], 0.5 op_sel_hi:[1,0]
	v_pk_mul_f32 v[200:201], v[120:121], 0.5 op_sel_hi:[1,0]
	v_pk_mul_f32 v[204:205], v[118:119], 0.5 op_sel_hi:[1,0]
	v_pk_mul_f32 v[206:207], v[116:117], 0.5 op_sel_hi:[1,0]
	v_pk_mul_f32 v[208:209], v[114:115], 0.5 op_sel_hi:[1,0]
	v_pk_mul_f32 v[210:211], v[96:97], 0.5 op_sel_hi:[1,0]
	v_pk_mul_f32 v[212:213], v[94:95], 0.5 op_sel_hi:[1,0]
	v_pk_mul_f32 v[216:217], v[88:89], 0.5 op_sel_hi:[1,0]
	v_pk_mul_f32 v[218:219], v[86:87], 0.5 op_sel_hi:[1,0]
	v_pk_mul_f32 v[174:175], v[108:109], 0.5 op_sel_hi:[1,0]
	v_pk_mul_f32 v[176:177], v[106:107], 0.5 op_sel_hi:[1,0]
	v_pk_mul_f32 v[178:179], v[100:101], 0.5 op_sel_hi:[1,0]
	v_pk_mul_f32 v[180:181], v[98:99], 0.5 op_sel_hi:[1,0]
	v_pk_mul_f32 v[182:183], v[80:81], 0.5 op_sel_hi:[1,0]
	v_pk_mul_f32 v[184:185], v[78:79], 0.5 op_sel_hi:[1,0]
	v_pk_mul_f32 v[186:187], v[76:77], 0.5 op_sel_hi:[1,0]
	v_pk_mul_f32 v[188:189], v[74:75], 0.5 op_sel_hi:[1,0]
	v_pk_mul_f32 v[158:159], v[92:93], 0.5 op_sel_hi:[1,0]
	v_pk_mul_f32 v[160:161], v[90:91], 0.5 op_sel_hi:[1,0]
	v_pk_mul_f32 v[162:163], v[84:85], 0.5 op_sel_hi:[1,0]
	v_pk_mul_f32 v[164:165], v[82:83], 0.5 op_sel_hi:[1,0]
	v_pk_mul_f32 v[166:167], v[72:73], 0.5 op_sel_hi:[1,0]
	v_pk_mul_f32 v[168:169], v[70:71], 0.5 op_sel_hi:[1,0]
	v_pk_mul_f32 v[170:171], v[68:69], 0.5 op_sel_hi:[1,0]
	v_pk_mul_f32 v[172:173], v[66:67], 0.5 op_sel_hi:[1,0]
	v_pk_mul_f32 v[154:155], v[44:45], 0.5 op_sel_hi:[1,0]
	v_pk_mul_f32 v[152:153], v[42:43], 0.5 op_sel_hi:[1,0]
	v_pk_mul_f32 v[150:151], v[48:49], 0.5 op_sel_hi:[1,0]
	v_pk_mul_f32 v[148:149], v[46:47], 0.5 op_sel_hi:[1,0]
	v_pk_mul_f32 v[146:147], v[60:61], 0.5 op_sel_hi:[1,0]
	v_pk_mul_f32 v[144:145], v[58:59], 0.5 op_sel_hi:[1,0]
	v_pk_mul_f32 v[142:143], v[64:65], 0.5 op_sel_hi:[1,0]
	v_pk_mul_f32 v[140:141], v[62:63], 0.5 op_sel_hi:[1,0]
	v_pk_mul_f32 v[128:129], v[28:29], 0.5 op_sel_hi:[1,0]
	v_pk_mul_f32 v[126:127], v[26:27], 0.5 op_sel_hi:[1,0]
	v_pk_mul_f32 v[124:125], v[32:33], 0.5 op_sel_hi:[1,0]
	v_pk_mul_f32 v[122:123], v[30:31], 0.5 op_sel_hi:[1,0]
	v_pk_mul_f32 v[120:121], v[52:53], 0.5 op_sel_hi:[1,0]
	v_pk_mul_f32 v[118:119], v[50:51], 0.5 op_sel_hi:[1,0]
	v_pk_mul_f32 v[116:117], v[56:57], 0.5 op_sel_hi:[1,0]
	v_pk_mul_f32 v[114:115], v[54:55], 0.5 op_sel_hi:[1,0]
	v_pk_mul_f32 v[112:113], v[12:13], 0.5 op_sel_hi:[1,0]
	v_pk_mul_f32 v[110:111], v[10:11], 0.5 op_sel_hi:[1,0]
	v_pk_mul_f32 v[108:109], v[16:17], 0.5 op_sel_hi:[1,0]
	v_pk_mul_f32 v[106:107], v[14:15], 0.5 op_sel_hi:[1,0]
	v_pk_mul_f32 v[104:105], v[36:37], 0.5 op_sel_hi:[1,0]
	v_pk_mul_f32 v[102:103], v[34:35], 0.5 op_sel_hi:[1,0]
	v_pk_mul_f32 v[100:101], v[40:41], 0.5 op_sel_hi:[1,0]
	v_pk_mul_f32 v[98:99], v[38:39], 0.5 op_sel_hi:[1,0]
	v_pk_mul_f32 v[96:97], v[4:5], 0.5 op_sel_hi:[1,0]
	v_pk_mul_f32 v[94:95], v[2:3], 0.5 op_sel_hi:[1,0]
	v_pk_mul_f32 v[92:93], v[8:9], 0.5 op_sel_hi:[1,0]
	v_pk_mul_f32 v[90:91], v[6:7], 0.5 op_sel_hi:[1,0]
	v_pk_mul_f32 v[88:89], v[20:21], 0.5 op_sel_hi:[1,0]
	v_pk_mul_f32 v[86:87], v[18:19], 0.5 op_sel_hi:[1,0]
	v_pk_mul_f32 v[84:85], v[24:25], 0.5 op_sel_hi:[1,0]
	v_pk_mul_f32 v[82:83], v[22:23], 0.5 op_sel_hi:[1,0]

; #define PG8_WAIT_V(n) asm volatile("s_waitcnt vmcnt(" #n ")" ::: "memory")
; #define PG8_BAR __builtin_amdgcn_s_barrier()
; template <class Epi, class Sched, bool ALIGN_EPI>
; __device__ __forceinline__ void gemm_phase(PG8_LAS unsigned char* lds, const Gemm g, const Sched& S, const Epi& E) {
;     ...
;     PG8_WAIT_V(0);
;     if constexpr (!ALIGN_EPI) { if (wr == 0) PG8_BAR; }
;     PG8_BAR;
.LBB0_352:
	s_waitcnt vmcnt(0)
	v_readlane_b32 s26, v255, 10
	v_readlane_b32 s24, v255, 18
	s_cmpk_gt_u32 s10, 0xff
	v_readlane_b32 s27, v255, 11
	v_readlane_b32 s25, v255, 19
	v_mov_b32_e32 v243, 0xc0
	v_mov_b32_e32 v246, 5
	v_mov_b32_e32 v249, 0xc8
	s_cbranch_scc1 .LBB0_354
	v_readlane_b32 s98, v255, 43
	s_mov_b32 s99, 0
	s_nop 1
	v_writelane_b32 v255, s99, 43
	s_cmp_eq_u32 s98, 1
	s_cbranch_scc1 .LBB0_354
	s_barrier
